# phase-0 bf16 x stores nontemporal
# speedup vs baseline: 1.0233x; 1.0028x over previous
.Lp0_xloop:
	s_cmp_eq_u32 s50, 0
	s_cbranch_scc1 .Lp0_xtail0
	s_cmpk_lt_u32 s3, 0x1000
	s_cselect_b32 s6, s56, s58
	s_cselect_b32 s7, s57, s59
	s_cselect_b32 s2, 0, 0x1000
	s_sub_u32 s2, s3, s2
	s_lshr_b32 s1, s2, 18
	s_lshl_b32 s2, s2, 14
	s_add_u32 s20, s6, s2
	s_addc_u32 s21, s7, s1
	global_load_dwordx4 v[48:51], v4, s[20:21] nt
	global_load_dwordx4 v[52:55], v4, s[20:21] offset:16 nt
	s_add_u32 s20, s20, 0x4000
	s_addc_u32 s21, s21, 0
	global_load_dwordx4 v[56:59], v4, s[20:21] nt
	global_load_dwordx4 v[60:63], v4, s[20:21] offset:16 nt
	s_add_u32 s3, s3, 2
	s_sub_u32 s50, s50, 1
	s_waitcnt vmcnt(8)
	v_cvt_pk_bf16_f32 v80, v16, v17
	v_cvt_pk_bf16_f32 v81, v18, v19
	v_cvt_pk_bf16_f32 v82, v20, v21
	v_cvt_pk_bf16_f32 v83, v22, v23
	v_cvt_pk_bf16_f32 v84, v24, v25
	v_cvt_pk_bf16_f32 v85, v26, v27
	v_cvt_pk_bf16_f32 v86, v28, v29
	v_cvt_pk_bf16_f32 v87, v30, v31
	global_store_dwordx4 v5, v[80:83], s[48:49] nt
	global_store_dwordx4 v12, v[84:87], s[48:49] nt
	s_add_u32 s48, s48, 0x4000
	s_addc_u32 s49, s49, 0
	s_cmp_eq_u32 s50, 0
	s_cbranch_scc1 .Lp0_xtail1
	s_cmpk_lt_u32 s3, 0x1000
	s_cselect_b32 s6, s56, s58
	s_cselect_b32 s7, s57, s59
	s_cselect_b32 s2, 0, 0x1000
	s_sub_u32 s2, s3, s2
	s_lshr_b32 s1, s2, 18
	s_lshl_b32 s2, s2, 14
	s_add_u32 s16, s6, s2
	s_addc_u32 s17, s7, s1
	global_load_dwordx4 v[16:19], v4, s[16:17] nt
	global_load_dwordx4 v[20:23], v4, s[16:17] offset:16 nt
	s_add_u32 s16, s16, 0x4000
	s_addc_u32 s17, s17, 0
	global_load_dwordx4 v[24:27], v4, s[16:17] nt
	global_load_dwordx4 v[28:31], v4, s[16:17] offset:16 nt
	s_add_u32 s3, s3, 2
	s_sub_u32 s50, s50, 1
	s_waitcnt vmcnt(8)
	v_cvt_pk_bf16_f32 v80, v32, v33
	v_cvt_pk_bf16_f32 v81, v34, v35
	v_cvt_pk_bf16_f32 v82, v36, v37
	v_cvt_pk_bf16_f32 v83, v38, v39
	v_cvt_pk_bf16_f32 v84, v40, v41
	v_cvt_pk_bf16_f32 v85, v42, v43
	v_cvt_pk_bf16_f32 v86, v44, v45
	v_cvt_pk_bf16_f32 v87, v46, v47
	global_store_dwordx4 v5, v[80:83], s[48:49] nt
	global_store_dwordx4 v12, v[84:87], s[48:49] nt
	s_add_u32 s48, s48, 0x4000
	s_addc_u32 s49, s49, 0
	s_cmp_eq_u32 s50, 0
	s_cbranch_scc1 .Lp0_xtail2
	s_cmpk_lt_u32 s3, 0x1000
	s_cselect_b32 s6, s56, s58
	s_cselect_b32 s7, s57, s59
	s_cselect_b32 s2, 0, 0x1000
	s_sub_u32 s2, s3, s2
	s_lshr_b32 s1, s2, 18
	s_lshl_b32 s2, s2, 14
	s_add_u32 s18, s6, s2
	s_addc_u32 s19, s7, s1
	global_load_dwordx4 v[32:35], v4, s[18:19] nt
	global_load_dwordx4 v[36:39], v4, s[18:19] offset:16 nt
	s_add_u32 s18, s18, 0x4000
	s_addc_u32 s19, s19, 0
	global_load_dwordx4 v[40:43], v4, s[18:19] nt
	global_load_dwordx4 v[44:47], v4, s[18:19] offset:16 nt
	s_add_u32 s3, s3, 2
	s_sub_u32 s50, s50, 1
	s_waitcnt vmcnt(8)
	v_cvt_pk_bf16_f32 v80, v48, v49
	v_cvt_pk_bf16_f32 v81, v50, v51
	v_cvt_pk_bf16_f32 v82, v52, v53
	v_cvt_pk_bf16_f32 v83, v54, v55
	v_cvt_pk_bf16_f32 v84, v56, v57
	v_cvt_pk_bf16_f32 v85, v58, v59
	v_cvt_pk_bf16_f32 v86, v60, v61
	v_cvt_pk_bf16_f32 v87, v62, v63
	global_store_dwordx4 v5, v[80:83], s[48:49] nt
	global_store_dwordx4 v12, v[84:87], s[48:49] nt
	s_add_u32 s48, s48, 0x4000
	s_addc_u32 s49, s49, 0
	s_branch .Lp0_xloop
.Lp0_xtail0:
	s_waitcnt vmcnt(4)
	v_cvt_pk_bf16_f32 v80, v16, v17
	v_cvt_pk_bf16_f32 v81, v18, v19
	v_cvt_pk_bf16_f32 v82, v20, v21
	v_cvt_pk_bf16_f32 v83, v22, v23
	v_cvt_pk_bf16_f32 v84, v24, v25
	v_cvt_pk_bf16_f32 v85, v26, v27
	v_cvt_pk_bf16_f32 v86, v28, v29
	v_cvt_pk_bf16_f32 v87, v30, v31
	global_store_dwordx4 v5, v[80:83], s[48:49] nt
	global_store_dwordx4 v12, v[84:87], s[48:49] nt
	s_add_u32 s48, s48, 0x4000
	s_addc_u32 s49, s49, 0
	s_waitcnt vmcnt(0)
	v_cvt_pk_bf16_f32 v80, v32, v33
	v_cvt_pk_bf16_f32 v81, v34, v35
	v_cvt_pk_bf16_f32 v82, v36, v37
	v_cvt_pk_bf16_f32 v83, v38, v39
	v_cvt_pk_bf16_f32 v84, v40, v41
	v_cvt_pk_bf16_f32 v85, v42, v43
	v_cvt_pk_bf16_f32 v86, v44, v45
	v_cvt_pk_bf16_f32 v87, v46, v47
	global_store_dwordx4 v5, v[80:83], s[48:49] nt
	global_store_dwordx4 v12, v[84:87], s[48:49] nt
	s_add_u32 s48, s48, 0x4000
	s_addc_u32 s49, s49, 0
	s_branch .Lp0_stzero
.Lp0_xtail1:
	s_waitcnt vmcnt(4)
	v_cvt_pk_bf16_f32 v80, v32, v33
	v_cvt_pk_bf16_f32 v81, v34, v35
	v_cvt_pk_bf16_f32 v82, v36, v37
	v_cvt_pk_bf16_f32 v83, v38, v39
	v_cvt_pk_bf16_f32 v84, v40, v41
	v_cvt_pk_bf16_f32 v85, v42, v43
	v_cvt_pk_bf16_f32 v86, v44, v45
	v_cvt_pk_bf16_f32 v87, v46, v47
	global_store_dwordx4 v5, v[80:83], s[48:49] nt
	global_store_dwordx4 v12, v[84:87], s[48:49] nt
	s_add_u32 s48, s48, 0x4000
	s_addc_u32 s49, s49, 0
	s_waitcnt vmcnt(0)
	v_cvt_pk_bf16_f32 v80, v48, v49
	v_cvt_pk_bf16_f32 v81, v50, v51
	v_cvt_pk_bf16_f32 v82, v52, v53
	v_cvt_pk_bf16_f32 v83, v54, v55
	v_cvt_pk_bf16_f32 v84, v56, v57
	v_cvt_pk_bf16_f32 v85, v58, v59
	v_cvt_pk_bf16_f32 v86, v60, v61
	v_cvt_pk_bf16_f32 v87, v62, v63
	global_store_dwordx4 v5, v[80:83], s[48:49] nt
	global_store_dwordx4 v12, v[84:87], s[48:49] nt
	s_add_u32 s48, s48, 0x4000
	s_addc_u32 s49, s49, 0
	s_branch .Lp0_stzero
.Lp0_xtail2:
	s_waitcnt vmcnt(4)
	v_cvt_pk_bf16_f32 v80, v48, v49
	v_cvt_pk_bf16_f32 v81, v50, v51
	v_cvt_pk_bf16_f32 v82, v52, v53
	v_cvt_pk_bf16_f32 v83, v54, v55
	v_cvt_pk_bf16_f32 v84, v56, v57
	v_cvt_pk_bf16_f32 v85, v58, v59
	v_cvt_pk_bf16_f32 v86, v60, v61
	v_cvt_pk_bf16_f32 v87, v62, v63
	global_store_dwordx4 v5, v[80:83], s[48:49] nt
	global_store_dwordx4 v12, v[84:87], s[48:49] nt
	s_add_u32 s48, s48, 0x4000
	s_addc_u32 s49, s49, 0
	s_waitcnt vmcnt(0)
	v_cvt_pk_bf16_f32 v80, v16, v17
	v_cvt_pk_bf16_f32 v81, v18, v19
	v_cvt_pk_bf16_f32 v82, v20, v21
	v_cvt_pk_bf16_f32 v83, v22, v23
	v_cvt_pk_bf16_f32 v84, v24, v25
	v_cvt_pk_bf16_f32 v85, v26, v27
	v_cvt_pk_bf16_f32 v86, v28, v29
	v_cvt_pk_bf16_f32 v87, v30, v31
	global_store_dwordx4 v5, v[80:83], s[48:49] nt
	global_store_dwordx4 v12, v[84:87], s[48:49] nt
	s_add_u32 s48, s48, 0x4000
	s_addc_u32 s49, s49, 0
	s_branch .Lp0_stzero
